# barrier: XCD leader no longer waits for its own release atomic (on top of early invalidate + selective write-back)
# speedup vs baseline: 1.0083x; 1.0083x over previous
.Lxb_release:
	global_atomic_add v5, v228, s[12:13]
	s_branch .LBB0_10
